# sample ffn-up task: all 32 operand loads first, per step sum of squares + pack + value/gate MFMA (was three waits per step)
# baseline (speedup 1.0000x reference)
; DEV unsigned pk2(float lo, float hi) { return (unsigned)f2bf(lo) | ((unsigned)f2bf(hi) << 16); }
; #define LAS __attribute__((address_space(3)))
; template <bool F32A, bool PAIR, class Epi> DEV void sgemm_wg(const void* Aptr, int lda, const bf16_t* Bt, int ldb, int K, int n0, int n1, int wave, int lane, LAS float* red, Epi epi) {
;     ...
;     for (int k = kb; k < kb + kper; k += 16) {
;         bf16x8 a;
;         if (F32A) { const float* ap = (const float*)Aptr + (size_t)r32 * lda + k + 8 * hi; const f32x4 x0 = *(const f32x4*)ap, x1 = *(const f32x4*)(ap + 4);
;             ss += (x0.x * x0.x + x0.y * x0.y) + (x0.z * x0.z + x0.w * x0.w) + (x1.x * x1.x + x1.y * x1.y) + (x1.z * x1.z + x1.w * x1.w);
;             u32x4 w; w.x = pk2(x0.x, x0.y); w.y = pk2(x0.z, x0.w); w.z = pk2(x1.x, x1.y); w.w = pk2(x1.z, x1.w); a = __builtin_bit_cast(bf16x8, w); }
;         else a = *(const bf16x8*)((const bf16_t*)Aptr + (size_t)r32 * lda + k + 8 * hi);
;         acc0 = __builtin_amdgcn_mfma_f32_32x32x16_bf16(a, *(const bf16x8*)(bp0 + k), acc0, 0, 0, 0);
;         if (PAIR) acc1 = __builtin_amdgcn_mfma_f32_32x32x16_bf16(a, *(const bf16x8*)(bp1 + k), acc1, 0, 0, 0);
;     }
; __global__ void __launch_bounds__(512, 2) mk_fwd(MKArgs args) {
;     ...
;               for (int k = G - 1 - bx; k < DFF / 32; k += G) { const int pv = 256 * (k >> 2) + 32 * (k & 3);
;                 sgemm_wg<true, true>(xs, DM, (const bf16_t*)(wl + WL_FFI), DM, DM, pv, pv + 128, wave, lane, (LAS float*)(ldsl + RING_OFF), [&](int row, int cc, float v, float gt, float ssq) {
.LBB0_2082:
	s_and_b32 s6, s21, 0xffffff00
	s_and_b32 s7, s25, 0x60
	s_or_b32 s6, s6, s7
	v_or_b32_e32 v2, s6, v52
	v_ashrrev_i32_e32 v3, 31, v2
	v_lshlrev_b64 v[6:7], 11, v[2:3]
	v_or_b32_e32 v2, s6, v53
	v_ashrrev_i32_e32 v3, 31, v2
	s_waitcnt vmcnt(0)
	v_lshlrev_b64 v[22:23], 11, v[2:3]
	s_barrier
	v_lshl_add_u64 v[42:43], v[50:51], 0, v[6:7]
	v_lshl_add_u64 v[40:41], v[50:51], 0, v[22:23]
	global_load_dwordx4 v[76:79], v[44:45], off
	global_load_dwordx4 v[80:83], v[44:45], off offset:16
	global_load_dwordx4 v[84:87], v[44:45], off offset:64
	global_load_dwordx4 v[88:91], v[44:45], off offset:80
	global_load_dwordx4 v[92:95], v[44:45], off offset:128
	global_load_dwordx4 v[96:99], v[44:45], off offset:144
	global_load_dwordx4 v[100:103], v[44:45], off offset:192
	global_load_dwordx4 v[104:107], v[44:45], off offset:208
	global_load_dwordx4 v[108:111], v[44:45], off offset:256
	global_load_dwordx4 v[112:115], v[44:45], off offset:272
	global_load_dwordx4 v[116:119], v[44:45], off offset:320
	global_load_dwordx4 v[120:123], v[44:45], off offset:336
	global_load_dwordx4 v[124:127], v[44:45], off offset:384
	global_load_dwordx4 v[128:131], v[44:45], off offset:400
	global_load_dwordx4 v[132:135], v[44:45], off offset:448
	global_load_dwordx4 v[136:139], v[44:45], off offset:464
	global_load_dwordx4 v[140:143], v[42:43], off
	global_load_dwordx4 v[172:175], v[40:41], off
	global_load_dwordx4 v[144:147], v[42:43], off offset:32
	global_load_dwordx4 v[176:179], v[40:41], off offset:32
	global_load_dwordx4 v[148:151], v[42:43], off offset:64
	global_load_dwordx4 v[180:183], v[40:41], off offset:64
	global_load_dwordx4 v[152:155], v[42:43], off offset:96
	global_load_dwordx4 v[184:187], v[40:41], off offset:96
	global_load_dwordx4 v[156:159], v[42:43], off offset:128
	global_load_dwordx4 v[188:191], v[40:41], off offset:128
	global_load_dwordx4 v[160:163], v[42:43], off offset:160
	global_load_dwordx4 v[192:195], v[40:41], off offset:160
	global_load_dwordx4 v[164:167], v[42:43], off offset:192
	global_load_dwordx4 v[196:199], v[40:41], off offset:192
	global_load_dwordx4 v[168:171], v[42:43], off offset:224
	global_load_dwordx4 v[200:203], v[40:41], off offset:224
	v_mov_b32_e32 v204, 0
	s_waitcnt vmcnt(14)
	v_mul_f32_e32 v205, v77, v77
	v_mul_f32_e32 v206, v79, v79
	v_fmac_f32_e32 v205, v76, v76
	v_fmac_f32_e32 v206, v78, v78
	v_add_f32_e32 v205, v205, v206
	v_mul_f32_e32 v206, v81, v81
	v_fmac_f32_e32 v206, v80, v80
	v_add_f32_e32 v205, v205, v206
	v_mul_f32_e32 v206, v83, v83
	v_fmac_f32_e32 v206, v82, v82
	v_add_f32_e32 v205, v206, v205
	v_add_f32_e32 v204, v204, v205
	v_cvt_pk_bf16_f32 v76, v76, v77
	v_cvt_pk_bf16_f32 v77, v78, v79
	v_cvt_pk_bf16_f32 v78, v80, v81
	v_cvt_pk_bf16_f32 v79, v82, v83
	s_nop 1
	v_mfma_f32_32x32x16_bf16 v[2:17], v[76:79], v[140:143], 0
	v_mfma_f32_32x32x16_bf16 v[18:33], v[76:79], v[172:175], 0
	s_waitcnt vmcnt(12)
	v_mul_f32_e32 v205, v85, v85
	v_mul_f32_e32 v206, v87, v87
	v_fmac_f32_e32 v205, v84, v84
	v_fmac_f32_e32 v206, v86, v86
	v_add_f32_e32 v205, v205, v206
	v_mul_f32_e32 v206, v89, v89
	v_fmac_f32_e32 v206, v88, v88
	v_add_f32_e32 v205, v205, v206
	v_mul_f32_e32 v206, v91, v91
	v_fmac_f32_e32 v206, v90, v90
	v_add_f32_e32 v205, v206, v205
	v_add_f32_e32 v204, v204, v205
	v_cvt_pk_bf16_f32 v84, v84, v85
	v_cvt_pk_bf16_f32 v85, v86, v87
	v_cvt_pk_bf16_f32 v86, v88, v89
	v_cvt_pk_bf16_f32 v87, v90, v91
	s_nop 1
	v_mfma_f32_32x32x16_bf16 v[2:17], v[84:87], v[144:147], v[2:17]
	v_mfma_f32_32x32x16_bf16 v[18:33], v[84:87], v[176:179], v[18:33]
	s_waitcnt vmcnt(10)
	v_mul_f32_e32 v205, v93, v93
	v_mul_f32_e32 v206, v95, v95
	v_fmac_f32_e32 v205, v92, v92
	v_fmac_f32_e32 v206, v94, v94
	v_add_f32_e32 v205, v205, v206
	v_mul_f32_e32 v206, v97, v97
	v_fmac_f32_e32 v206, v96, v96
	v_add_f32_e32 v205, v205, v206
	v_mul_f32_e32 v206, v99, v99
	v_fmac_f32_e32 v206, v98, v98
	v_add_f32_e32 v205, v206, v205
	v_add_f32_e32 v204, v204, v205
	v_cvt_pk_bf16_f32 v92, v92, v93
	v_cvt_pk_bf16_f32 v93, v94, v95
	v_cvt_pk_bf16_f32 v94, v96, v97
	v_cvt_pk_bf16_f32 v95, v98, v99
	s_nop 1
	v_mfma_f32_32x32x16_bf16 v[2:17], v[92:95], v[148:151], v[2:17]
	v_mfma_f32_32x32x16_bf16 v[18:33], v[92:95], v[180:183], v[18:33]
	s_waitcnt vmcnt(8)
; DEV unsigned pk2(float lo, float hi) { return (unsigned)f2bf(lo) | ((unsigned)f2bf(hi) << 16); }
; DEV float shfl_xor_(float v, int m) { return __builtin_bit_cast(float, __builtin_amdgcn_ds_bpermute((lane_id() ^ m) << 2, __builtin_bit_cast(int, v))); }
; #define LAS __attribute__((address_space(3)))
; template <bool F32A, bool PAIR, class Epi> DEV void sgemm_wg(const void* Aptr, int lda, const bf16_t* Bt, int ldb, int K, int n0, int n1, int wave, int lane, LAS float* red, Epi epi) {
;     ...
;     for (int k = kb; k < kb + kper; k += 16) {
;         bf16x8 a;
;         if (F32A) { const float* ap = (const float*)Aptr + (size_t)r32 * lda + k + 8 * hi; const f32x4 x0 = *(const f32x4*)ap, x1 = *(const f32x4*)(ap + 4);
;             ss += (x0.x * x0.x + x0.y * x0.y) + (x0.z * x0.z + x0.w * x0.w) + (x1.x * x1.x + x1.y * x1.y) + (x1.z * x1.z + x1.w * x1.w);
;             u32x4 w; w.x = pk2(x0.x, x0.y); w.y = pk2(x0.z, x0.w); w.z = pk2(x1.x, x1.y); w.w = pk2(x1.z, x1.w); a = __builtin_bit_cast(bf16x8, w); }
;         else a = *(const bf16x8*)((const bf16_t*)Aptr + (size_t)r32 * lda + k + 8 * hi);
;         acc0 = __builtin_amdgcn_mfma_f32_32x32x16_bf16(a, *(const bf16x8*)(bp0 + k), acc0, 0, 0, 0);
;         if (PAIR) acc1 = __builtin_amdgcn_mfma_f32_32x32x16_bf16(a, *(const bf16x8*)(bp1 + k), acc1, 0, 0, 0);
;     }
;     LAS float* ssw = red + 2 * 8 * 1024;
; #pragma unroll
;     for (int r = 0; r < 16; ++r) { red[(wave * 16 + r) * 64 + lane] = acc0[r]; if (PAIR) red[8 * 1024 + (wave * 16 + r) * 64 + lane] = acc1[r]; }
;     if (F32A) { ss += shfl_xor_(ss, 32); if (lane < 32) ssw[wave * 32 + lane] = ss; }
	v_mul_f32_e32 v205, v101, v101
	v_mul_f32_e32 v206, v103, v103
	v_fmac_f32_e32 v205, v100, v100
	v_fmac_f32_e32 v206, v102, v102
	v_add_f32_e32 v205, v205, v206
	v_mul_f32_e32 v206, v105, v105
	v_fmac_f32_e32 v206, v104, v104
	v_add_f32_e32 v205, v205, v206
	v_mul_f32_e32 v206, v107, v107
	v_fmac_f32_e32 v206, v106, v106
	v_add_f32_e32 v205, v206, v205
	v_add_f32_e32 v204, v204, v205
	v_cvt_pk_bf16_f32 v100, v100, v101
	v_cvt_pk_bf16_f32 v101, v102, v103
	v_cvt_pk_bf16_f32 v102, v104, v105
	v_cvt_pk_bf16_f32 v103, v106, v107
	s_nop 1
	v_mfma_f32_32x32x16_bf16 v[2:17], v[100:103], v[152:155], v[2:17]
	v_mfma_f32_32x32x16_bf16 v[18:33], v[100:103], v[184:187], v[18:33]
	s_waitcnt vmcnt(6)
	v_mul_f32_e32 v205, v109, v109
	v_mul_f32_e32 v206, v111, v111
	v_fmac_f32_e32 v205, v108, v108
	v_fmac_f32_e32 v206, v110, v110
	v_add_f32_e32 v205, v205, v206
	v_mul_f32_e32 v206, v113, v113
	v_fmac_f32_e32 v206, v112, v112
	v_add_f32_e32 v205, v205, v206
	v_mul_f32_e32 v206, v115, v115
	v_fmac_f32_e32 v206, v114, v114
	v_add_f32_e32 v205, v206, v205
	v_add_f32_e32 v204, v204, v205
	v_cvt_pk_bf16_f32 v108, v108, v109
	v_cvt_pk_bf16_f32 v109, v110, v111
	v_cvt_pk_bf16_f32 v110, v112, v113
	v_cvt_pk_bf16_f32 v111, v114, v115
	s_nop 1
	v_mfma_f32_32x32x16_bf16 v[2:17], v[108:111], v[156:159], v[2:17]
	v_mfma_f32_32x32x16_bf16 v[18:33], v[108:111], v[188:191], v[18:33]
	s_waitcnt vmcnt(4)
	v_mul_f32_e32 v205, v117, v117
	v_mul_f32_e32 v206, v119, v119
	v_fmac_f32_e32 v205, v116, v116
	v_fmac_f32_e32 v206, v118, v118
	v_add_f32_e32 v205, v205, v206
	v_mul_f32_e32 v206, v121, v121
	v_fmac_f32_e32 v206, v120, v120
	v_add_f32_e32 v205, v205, v206
	v_mul_f32_e32 v206, v123, v123
	v_fmac_f32_e32 v206, v122, v122
	v_add_f32_e32 v205, v206, v205
	v_add_f32_e32 v204, v204, v205
	v_cvt_pk_bf16_f32 v116, v116, v117
	v_cvt_pk_bf16_f32 v117, v118, v119
	v_cvt_pk_bf16_f32 v118, v120, v121
	v_cvt_pk_bf16_f32 v119, v122, v123
	s_nop 1
	v_mfma_f32_32x32x16_bf16 v[2:17], v[116:119], v[160:163], v[2:17]
	v_mfma_f32_32x32x16_bf16 v[18:33], v[116:119], v[192:195], v[18:33]
	s_waitcnt vmcnt(2)
	v_mul_f32_e32 v205, v125, v125
	v_mul_f32_e32 v206, v127, v127
	v_fmac_f32_e32 v205, v124, v124
	v_fmac_f32_e32 v206, v126, v126
	v_add_f32_e32 v205, v205, v206
	v_mul_f32_e32 v206, v129, v129
	v_fmac_f32_e32 v206, v128, v128
	v_add_f32_e32 v205, v205, v206
	v_mul_f32_e32 v206, v131, v131
	v_fmac_f32_e32 v206, v130, v130
	v_add_f32_e32 v205, v206, v205
	v_add_f32_e32 v204, v204, v205
	v_cvt_pk_bf16_f32 v124, v124, v125
	v_cvt_pk_bf16_f32 v125, v126, v127
	v_cvt_pk_bf16_f32 v126, v128, v129
	v_cvt_pk_bf16_f32 v127, v130, v131
	s_nop 1
	v_mfma_f32_32x32x16_bf16 v[2:17], v[124:127], v[164:167], v[2:17]
	v_mfma_f32_32x32x16_bf16 v[18:33], v[124:127], v[196:199], v[18:33]
	s_waitcnt vmcnt(0)
	v_mul_f32_e32 v205, v133, v133
	v_mul_f32_e32 v206, v135, v135
	v_fmac_f32_e32 v205, v132, v132
	v_fmac_f32_e32 v206, v134, v134
	v_add_f32_e32 v205, v205, v206
	v_mul_f32_e32 v206, v137, v137
	v_fmac_f32_e32 v206, v136, v136
	v_add_f32_e32 v205, v205, v206
	v_mul_f32_e32 v206, v139, v139
	v_fmac_f32_e32 v206, v138, v138
	v_add_f32_e32 v205, v206, v205
	v_add_f32_e32 v204, v204, v205
	v_cvt_pk_bf16_f32 v132, v132, v133
	v_cvt_pk_bf16_f32 v133, v134, v135
	v_cvt_pk_bf16_f32 v134, v136, v137
	v_cvt_pk_bf16_f32 v135, v138, v139
	s_nop 1
	v_mfma_f32_32x32x16_bf16 v[2:17], v[132:135], v[168:171], v[2:17]
	v_mfma_f32_32x32x16_bf16 v[18:33], v[132:135], v[200:203], v[18:33]
	s_nop 9
	ds_write2st64_b32 v0, v2, v3 offset1:1
	s_nop 0
	ds_write2st64_b32 v0, v18, v19 offset0:128 offset1:129
	ds_write2st64_b32 v0, v4, v5 offset0:2 offset1:3
	ds_write2st64_b32 v0, v20, v21 offset0:130 offset1:131
	ds_write2st64_b32 v0, v6, v7 offset0:4 offset1:5
	ds_write2st64_b32 v0, v22, v23 offset0:132 offset1:133
	ds_write2st64_b32 v0, v8, v9 offset0:6 offset1:7
	ds_write2st64_b32 v0, v24, v25 offset0:134 offset1:135
	ds_write2st64_b32 v0, v10, v11 offset0:8 offset1:9
	ds_write2st64_b32 v0, v26, v27 offset0:136 offset1:137
	ds_write2st64_b32 v0, v12, v13 offset0:10 offset1:11
	ds_write2st64_b32 v0, v28, v29 offset0:138 offset1:139
	ds_write2st64_b32 v0, v14, v15 offset0:12 offset1:13
	ds_write2st64_b32 v0, v30, v31 offset0:140 offset1:141
	ds_write2st64_b32 v0, v16, v17 offset0:14 offset1:15
	ds_write2st64_b32 v0, v32, v33 offset0:142 offset1:143
	v_mov_b32_e32 v2, v204
	v_mbcnt_lo_u32_b32 v3, -1, 0
	v_mbcnt_hi_u32_b32 v3, -1, v3
	v_lshlrev_b32_e32 v3, 2, v3
	v_xor_b32_e32 v3, 0x80, v3
	ds_bpermute_b32 v3, v3, v2
	s_and_saveexec_b64 s[6:7], s[4:5]
	s_cbranch_execz .LBB0_2084
	s_waitcnt lgkmcnt(0)
	v_add_f32_e32 v2, v2, v3
	ds_write_b32 v54, v2
